# adds: attention next-ticket atomic issued at final step; P4 both halves run the K-midpoint gate scaling together (extra barrier pair)
# speedup vs baseline: 1.0051x; 1.0051x over previous
.LBB0_345:
	s_and_saveexec_b64 s[0:1], s[84:85]
	s_cbranch_execz .Ltick_skip
	v_mov_b32_e32 v190, 1
	global_atomic_add v190, v195, v190, s[88:89] offset:512 sc0
.Ltick_skip:
	s_or_b64 exec, exec, s[0:1]
	v_add_u32_e32 v112, s44, v214
	ds_read_b64_tr_b16 v[162:163], v112 offset:24576
	ds_read_b64_tr_b16 v[164:165], v112 offset:25088
	v_add_f32_e32 v113, v80, v81
	s_setprio 1
	s_waitcnt lgkmcnt(4)
	v_mfma_f32_32x32x16_bf16 v[32:47], v[158:161], v[126:129], v[32:47]
	s_setprio 0
	v_add_f32_e32 v113, v82, v113
	v_add_f32_e32 v113, v83, v113
	v_add_f32_e32 v113, v84, v113
	v_add_f32_e32 v113, v85, v113
	v_cvt_pk_bf16_f32 v142, v80, v81
	v_cvt_pk_bf16_f32 v143, v82, v83
	ds_read_b64_tr_b16 v[158:159], v112 offset:28672
	ds_read_b64_tr_b16 v[160:161], v112 offset:29184
	s_setprio 1
	s_waitcnt lgkmcnt(4)
	v_mfma_f32_32x32x16_bf16 v[48:63], v[154:157], v[126:129], v[48:63]
	s_setprio 0
	v_add_f32_e32 v80, v86, v113
	v_add_f32_e32 v80, v87, v80
	v_add_f32_e32 v80, v88, v80
	v_add_f32_e32 v80, v89, v80
	v_cvt_pk_bf16_f32 v144, v84, v85
	v_cvt_pk_bf16_f32 v145, v86, v87
	ds_read_b64_tr_b16 v[126:127], v112 offset:25600
	ds_read_b64_tr_b16 v[128:129], v112 offset:26112
	s_setprio 1
	v_mfma_f32_32x32x16_bf16 v[32:47], v[150:153], v[122:125], v[32:47]
	s_setprio 0
	v_add_f32_e32 v80, v90, v80
	v_add_f32_e32 v80, v91, v80
	v_add_f32_e32 v80, v92, v80
	v_add_f32_e32 v80, v93, v80
	v_cvt_pk_bf16_f32 v138, v88, v89
	v_cvt_pk_bf16_f32 v139, v90, v91
	ds_read_b64_tr_b16 v[88:89], v112 offset:29696
	ds_read_b64_tr_b16 v[90:91], v112 offset:30208
	s_setprio 1
	v_mfma_f32_32x32x16_bf16 v[48:63], v[146:149], v[122:125], v[48:63]
	s_setprio 0
	v_add_f32_e32 v80, v94, v80
	v_add_f32_e32 v80, v95, v80
	v_add_f32_e32 v80, v64, v80
	v_add_f32_e32 v80, v65, v80
	v_cvt_pk_bf16_f32 v140, v92, v93
	v_cvt_pk_bf16_f32 v141, v94, v95
	ds_read_b64_tr_b16 v[84:85], v112 offset:26624
	ds_read_b64_tr_b16 v[86:87], v112 offset:27136
	s_setprio 1
	v_mfma_f32_32x32x16_bf16 v[32:47], v[108:111], v[118:121], v[32:47]
	s_setprio 0
	v_add_f32_e32 v80, v66, v80
	v_add_f32_e32 v80, v67, v80
	v_add_f32_e32 v80, v68, v80
	v_add_f32_e32 v92, v69, v80
	v_cvt_pk_bf16_f32 v134, v64, v65
	v_cvt_pk_bf16_f32 v135, v66, v67
	ds_read_b64_tr_b16 v[80:81], v112 offset:30720
	ds_read_b64_tr_b16 v[82:83], v112 offset:31232
	s_setprio 1
	v_mfma_f32_32x32x16_bf16 v[48:63], v[100:103], v[118:121], v[48:63]
	s_setprio 0
	v_add_f32_e32 v64, v70, v92
	v_add_f32_e32 v64, v71, v64
	v_add_f32_e32 v64, v72, v64
	v_add_f32_e32 v64, v73, v64
	v_cvt_pk_bf16_f32 v136, v68, v69
	v_cvt_pk_bf16_f32 v137, v70, v71
	ds_read_b64_tr_b16 v[68:69], v112 offset:27648
	ds_read_b64_tr_b16 v[70:71], v112 offset:28160
	s_setprio 1
	v_mfma_f32_32x32x16_bf16 v[32:47], v[104:107], v[114:117], v[32:47]
	s_setprio 0
	v_add_f32_e32 v64, v74, v64
	v_add_f32_e32 v64, v75, v64
	v_add_f32_e32 v64, v76, v64
	v_add_f32_e32 v92, v77, v64
	v_cvt_pk_bf16_f32 v130, v72, v73
	v_cvt_pk_bf16_f32 v131, v74, v75
	ds_read_b64_tr_b16 v[64:65], v112 offset:31744
	ds_read_b64_tr_b16 v[66:67], v112 offset:32256
	s_setprio 1
	v_mfma_f32_32x32x16_bf16 v[48:63], v[96:99], v[114:117], v[48:63]
	s_setprio 0
	v_add_f32_e32 v72, v78, v92
	v_add_f32_e32 v72, v79, v72
	v_add_f32_e32 v99, 0, v72
	v_cvt_pk_bf16_f32 v132, v76, v77
	v_cvt_pk_bf16_f32 v133, v78, v79
	v_or_b32_e32 v72, 0xe0, v215
	v_cmp_le_u32_e32 vcc, v72, v201
	v_add_f32_e32 v78, v203, v99
	s_nop 2
	v_cndmask_b32_e32 v79, v254, v48, vcc
	v_cmp_lt_u32_e32 vcc, v217, v201
	s_nop 1
	v_cndmask_b32_e32 v92, v254, v33, vcc
	v_cmp_le_u32_e32 vcc, v217, v201
	s_nop 1
	v_cndmask_b32_e32 v93, v254, v32, vcc
	v_or_b32_e32 v32, 0xe1, v215
	v_cmp_le_u32_e32 vcc, v32, v201
	s_nop 1
	v_cndmask_b32_e32 v94, v254, v49, vcc
	v_cmp_le_u32_e32 vcc, v218, v201
	s_nop 1
	v_cndmask_b32_e32 v95, v254, v34, vcc
	v_cmp_le_u32_e32 vcc, v219, v201
	s_nop 1
	v_cndmask_b32_e32 v96, v254, v50, vcc
	v_cmp_le_u32_e32 vcc, v220, v201
	s_nop 1
	v_cndmask_b32_e32 v97, v254, v35, vcc
	v_cmp_le_u32_e32 vcc, v221, v201
	s_nop 1
	v_cndmask_b32_e32 v98, v254, v51, vcc
	v_cmp_le_u32_e32 vcc, v222, v201
	s_nop 1
	v_cndmask_b32_e32 v34, v254, v36, vcc
	v_cmp_le_u32_e32 vcc, v223, v201
	v_max_f32_e32 v36, v92, v92
	s_nop 0
	v_cndmask_b32_e32 v32, v254, v52, vcc
	v_cmp_le_u32_e32 vcc, v224, v201
	s_nop 1
	v_cndmask_b32_e32 v35, v254, v37, vcc
	v_cmp_le_u32_e32 vcc, v225, v201
	v_max_f32_e32 v37, v93, v93
	v_max_f32_e32 v36, v37, v36
	v_cndmask_b32_e32 v33, v254, v53, vcc
	v_cmp_le_u32_e32 vcc, v226, v201
	v_max3_f32 v37, v95, v97, v94
	v_max3_f32 v36, v36, v79, v96
	v_cndmask_b32_e32 v48, v254, v38, vcc
	v_cmp_le_u32_e32 vcc, v227, v201
	v_max3_f32 v36, v36, v98, v34
	v_max3_f32 v36, v36, v35, v32
	v_cndmask_b32_e32 v38, v254, v54, vcc
	v_cmp_le_u32_e32 vcc, v228, v201
	s_nop 1
	v_cndmask_b32_e32 v49, v254, v39, vcc
	v_cmp_le_u32_e32 vcc, v229, v201
	v_max3_f32 v37, v37, v48, v49
	s_nop 0
	v_cndmask_b32_e32 v39, v254, v55, vcc
	v_cmp_le_u32_e32 vcc, v230, v201
	v_max3_f32 v37, v37, v38, v39
	s_nop 0
	v_cndmask_b32_e32 v50, v254, v40, vcc
	v_cmp_le_u32_e32 vcc, v231, v201
	v_max3_f32 v36, v36, v33, v50
	s_nop 0
	v_cndmask_b32_e32 v40, v254, v56, vcc
	v_cmp_le_u32_e32 vcc, v232, v201
	s_nop 1
	v_cndmask_b32_e32 v51, v254, v41, vcc
	v_cmp_le_u32_e32 vcc, v233, v201
	v_max3_f32 v36, v36, v51, v40
	s_nop 0
	v_cndmask_b32_e32 v41, v254, v57, vcc
	v_cmp_le_u32_e32 vcc, v234, v201
	s_nop 1
	v_cndmask_b32_e32 v72, v254, v42, vcc
	v_cmp_le_u32_e32 vcc, v235, v201
	s_nop 1
	v_cndmask_b32_e32 v42, v254, v58, vcc
	v_cmp_le_u32_e32 vcc, v236, v201
	s_nop 1
	v_cndmask_b32_e32 v73, v254, v43, vcc
	v_cmp_le_u32_e32 vcc, v237, v201
	v_max3_f32 v37, v37, v72, v73
	s_nop 0
	v_cndmask_b32_e32 v43, v254, v59, vcc
	v_cmp_le_u32_e32 vcc, v238, v201
	v_max3_f32 v37, v37, v42, v43
	s_nop 0
	v_cndmask_b32_e32 v74, v254, v44, vcc
	v_cmp_le_u32_e32 vcc, v239, v201
	v_max3_f32 v36, v36, v41, v74
	s_nop 0
	v_cndmask_b32_e32 v44, v254, v60, vcc
	v_cmp_le_u32_e32 vcc, v240, v201
	s_nop 1
	v_cndmask_b32_e32 v75, v254, v45, vcc
	v_cmp_le_u32_e32 vcc, v241, v201
	v_max3_f32 v36, v36, v75, v44
	s_nop 0
	v_cndmask_b32_e32 v45, v254, v61, vcc
	v_cmp_le_u32_e32 vcc, v242, v201
	s_nop 1
	v_cndmask_b32_e32 v76, v254, v46, vcc
	v_cmp_le_u32_e32 vcc, v243, v201
	s_nop 1
	v_cndmask_b32_e32 v46, v254, v62, vcc
	v_cmp_le_u32_e32 vcc, v244, v201
	s_nop 1
	v_cndmask_b32_e32 v77, v254, v47, vcc
	v_cmp_le_u32_e32 vcc, v245, v201
	v_max3_f32 v37, v37, v76, v77
	s_nop 0
	v_cndmask_b32_e32 v47, v254, v63, vcc
	v_max3_f32 v37, v37, v46, v47
	v_max3_f32 v36, v36, v45, v37
	v_mov_b32_e32 v37, v36
	s_nop 1
	v_permlane32_swap_b32_e32 v36, v37
	v_max_f32_e32 v37, v37, v37
	v_max_f32_e32 v36, v36, v36
	v_max_f32_e32 v36, v36, v37
	v_sub_f32_e32 v36, v36, v206
	v_cmp_lt_f32_e32 vcc, s35, v36
	s_cmp_lg_u64 vcc, 0
	s_cselect_b64 s[0:1], -1, 0
	s_cbranch_vccz .LBB0_349
	v_max_f32_e32 v36, v36, v36
	v_max_f32_e32 v37, 0, v36
	v_exp_f32_e64 v36, -v37
	s_and_saveexec_b64 s[12:13], s[4:5]
	ds_write_b32 v199, v36 offset:49152
	s_or_b64 exec, exec, s[12:13]
	v_add_f32_e32 v206, v206, v37
	v_mul_f32_e32 v78, v78, v36

.Lconv_done:
	s_and_saveexec_b64 s[0:1], s[84:85]
	s_xor_b64 s[0:1], exec, s[0:1]
	s_cbranch_execz .LBB0_319
	s_mov_b64 s[12:13], exec
	v_mbcnt_lo_u32_b32 v0, s12, 0
	v_mbcnt_hi_u32_b32 v0, s13, v0
	v_cmp_eq_u32_e32 vcc, 0, v0
	s_and_saveexec_b64 s[10:11], vcc
	s_cbranch_execz .LBB0_318
	s_waitcnt vmcnt(0)
	v_mov_b32_e32 v1, v190
	s_branch .LBB0_318

.LBB0_503:
	s_cmpk_lg_i32 s40, 0x400
	s_cbranch_scc1 .LBB0_502
	s_and_b64 vcc, exec, s[16:17]
	s_cbranch_vccz .Lmid_align_a
	s_barrier
.Lmid_align_a:
	v_mov_b32_e32 v2, v174
	v_mov_b32_e32 v132, v172
	s_nop 0
	v_ashrrev_i32_e32 v3, 31, v2
	v_ashrrev_i32_e32 v133, 31, v132
	v_lshlrev_b64 v[2:3], 10, v[2:3]
	v_lshl_add_u64 v[2:3], v[2:3], 0, v[132:133]
	v_lshlrev_b64 v[2:3], 1, v[2:3]
	v_lshl_add_u64 v[132:133], s[12:13], 0, v[2:3]
	global_load_dwordx4 v[144:147], v[132:133], off
	v_lshl_add_u64 v[134:135], s[10:11], 0, v[2:3]
	global_load_dwordx4 v[140:143], v[134:135], off
	global_load_dwordx4 v[184:187], v[132:133], off offset:256
	global_load_dwordx4 v[188:191], v[134:135], off offset:256
	v_lshl_add_u64 v[132:133], v[2:3], 0, s[18:19]
	v_lshl_add_u64 v[134:135], s[12:13], 0, v[132:133]
	global_load_dwordx4 v[192:195], v[134:135], off
	v_lshl_add_u64 v[132:133], s[10:11], 0, v[132:133]
	global_load_dwordx4 v[136:139], v[132:133], off
	global_load_dwordx4 v[152:155], v[132:133], off offset:256
	global_load_dwordx4 v[196:199], v[134:135], off offset:256
	v_lshl_add_u64 v[148:149], v[2:3], 0, s[20:21]
	v_lshl_add_u64 v[200:201], s[10:11], 0, v[148:149]
	v_lshl_add_u64 v[202:203], s[12:13], 0, v[148:149]
	global_load_dwordx4 v[132:135], v[200:201], off
	global_load_dwordx4 v[148:151], v[202:203], off
	s_waitcnt vmcnt(0)
	v_lshlrev_b32_e32 v204, 16, v140
	v_lshlrev_b32_e32 v212, 16, v147
	v_and_b32_e32 v213, 0xffff0000, v147
	v_rcp_f32_e32 v212, v212
	v_rcp_f32_e32 v213, v213
	v_lshlrev_b32_e32 v208, 16, v146
	v_and_b32_e32 v209, 0xffff0000, v146
	v_lshlrev_b32_e32 v1, 16, v144
	v_rcp_f32_e32 v210, v208
	v_rcp_f32_e32 v211, v209
	v_and_b32_e32 v173, 0xffff0000, v144
	v_lshlrev_b32_e32 v175, 16, v145
	v_and_b32_e32 v207, 0xffff0000, v145
	v_lshlrev_b32_e32 v144, 16, v142
	v_and_b32_e32 v145, 0xffff0000, v142
	v_lshlrev_b32_e32 v142, 16, v143
	v_and_b32_e32 v143, 0xffff0000, v143
	v_lshlrev_b32_e32 v214, 16, v184
	v_and_b32_e32 v215, 0xffff0000, v184
	v_lshlrev_b32_e32 v146, 16, v188
	v_and_b32_e32 v147, 0xffff0000, v188
	v_lshlrev_b32_e32 v216, 16, v185
	v_and_b32_e32 v217, 0xffff0000, v185
	v_lshlrev_b32_e32 v184, 16, v189
	v_and_b32_e32 v185, 0xffff0000, v189
	v_lshlrev_b32_e32 v188, 16, v190
	v_and_b32_e32 v189, 0xffff0000, v190
	v_rcp_f32_e32 v190, v1
	v_lshlrev_b32_e32 v1, 16, v192
	v_rcp_f32_e32 v222, v1
	v_pk_mul_f32 v[142:143], v[212:213], v[142:143]
	v_lshlrev_b32_e32 v1, 16, v193
	v_rcp_f32_e32 v206, v175
	v_rcp_f32_e32 v207, v207
	v_pk_mul_f32 v[126:127], v[126:127], v[142:143]
	v_rcp_f32_e32 v142, v1
	v_and_b32_e32 v1, 0xffff0000, v193
	v_pk_mul_f32 v[144:145], v[210:211], v[144:145]
	v_rcp_f32_e32 v143, v1
	v_lshlrev_b32_e32 v1, 16, v194
	v_rcp_f32_e32 v214, v214
	v_rcp_f32_e32 v215, v215
	v_rcp_f32_e32 v216, v216
	v_rcp_f32_e32 v217, v217
	v_pk_mul_f32 v[124:125], v[124:125], v[144:145]
	v_rcp_f32_e32 v144, v1
	v_and_b32_e32 v1, 0xffff0000, v194
	v_and_b32_e32 v205, 0xffff0000, v140
	v_lshlrev_b32_e32 v140, 16, v141
	v_and_b32_e32 v141, 0xffff0000, v141
	v_rcp_f32_e32 v145, v1
	v_pk_mul_f32 v[140:141], v[206:207], v[140:141]
	v_lshlrev_b32_e32 v218, 16, v186
	v_pk_mul_f32 v[130:131], v[130:131], v[140:141]
	v_lshlrev_b32_e32 v140, 16, v136
	v_and_b32_e32 v141, 0xffff0000, v136
	v_lshlrev_b32_e32 v136, 16, v137
	v_and_b32_e32 v137, 0xffff0000, v137
	v_and_b32_e32 v219, 0xffff0000, v186
	v_lshlrev_b32_e32 v220, 16, v187
	v_and_b32_e32 v221, 0xffff0000, v187
	v_lshlrev_b32_e32 v186, 16, v191
	v_and_b32_e32 v187, 0xffff0000, v191
	v_rcp_f32_e32 v191, v173
	v_and_b32_e32 v173, 0xffff0000, v192
	v_pk_mul_f32 v[146:147], v[214:215], v[146:147]
	v_pk_mul_f32 v[184:185], v[216:217], v[184:185]
	v_pk_mul_f32 v[136:137], v[142:143], v[136:137]
	v_lshlrev_b32_e32 v142, 16, v138
	v_and_b32_e32 v143, 0xffff0000, v138
	v_lshlrev_b32_e32 v1, 16, v195
	v_pk_mul_f32 v[122:123], v[122:123], v[184:185]
	v_pk_mul_f32 v[120:121], v[120:121], v[146:147]
	v_rcp_f32_e32 v223, v173
	v_pk_mul_f32 v[142:143], v[144:145], v[142:143]
	v_rcp_f32_e32 v184, v1
	v_and_b32_e32 v1, 0xffff0000, v195
	global_load_dwordx4 v[144:147], v[202:203], off offset:256
	v_rcp_f32_e32 v185, v1
	v_pk_mul_f32 v[140:141], v[222:223], v[140:141]
	v_lshlrev_b32_e32 v138, 16, v139
	v_and_b32_e32 v139, 0xffff0000, v139
	v_lshlrev_b32_e32 v1, 16, v196
	v_rcp_f32_e32 v218, v218
	v_rcp_f32_e32 v219, v219
	v_pk_mul_f32 v[184:185], v[184:185], v[138:139]
	v_pk_mul_f32 v[114:115], v[114:115], v[136:137]
	global_load_dwordx4 v[136:139], v[200:201], off offset:256
	v_pk_mul_f32 v[112:113], v[112:113], v[140:141]
	v_rcp_f32_e32 v140, v1
	v_and_b32_e32 v1, 0xffff0000, v196
	v_rcp_f32_e32 v141, v1
	v_pk_mul_f32 v[188:189], v[218:219], v[188:189]
	v_pk_mul_f32 v[108:109], v[108:109], v[142:143]
	v_lshlrev_b32_e32 v142, 16, v152
	v_and_b32_e32 v143, 0xffff0000, v152
	v_lshlrev_b32_e32 v1, 16, v197
	v_pk_mul_f32 v[116:117], v[116:117], v[188:189]
	v_pk_mul_f32 v[188:189], v[140:141], v[142:143]
	v_rcp_f32_e32 v140, v1
	v_and_b32_e32 v1, 0xffff0000, v197
	v_rcp_f32_e32 v141, v1
	v_lshlrev_b32_e32 v1, 16, v198
	v_rcp_f32_e32 v220, v220
	v_rcp_f32_e32 v221, v221
	v_rcp_f32_e32 v152, v1
	v_and_b32_e32 v1, 0xffff0000, v198
	v_lshlrev_b32_e32 v142, 16, v153
	v_and_b32_e32 v143, 0xffff0000, v153
	v_rcp_f32_e32 v153, v1
	v_pk_mul_f32 v[190:191], v[190:191], v[204:205]
	v_pk_mul_f32 v[186:187], v[220:221], v[186:187]
	v_pk_mul_f32 v[128:129], v[128:129], v[190:191]
	v_lshl_add_u64 v[190:191], v[2:3], 0, s[22:23]
	v_pk_mul_f32 v[140:141], v[140:141], v[142:143]
	v_lshlrev_b32_e32 v142, 16, v154
	v_and_b32_e32 v143, 0xffff0000, v154
	v_lshlrev_b32_e32 v1, 16, v199
	v_lshl_add_u64 v[192:193], s[12:13], 0, v[190:191]
	v_pk_mul_f32 v[118:119], v[118:119], v[186:187]
	v_pk_mul_f32 v[110:111], v[110:111], v[184:185]
	v_pk_mul_f32 v[152:153], v[152:153], v[142:143]
	v_rcp_f32_e32 v142, v1
	v_and_b32_e32 v1, 0xffff0000, v199
	global_load_dwordx4 v[184:187], v[192:193], off
	v_rcp_f32_e32 v143, v1
	v_lshlrev_b32_e32 v154, 16, v155
	v_and_b32_e32 v155, 0xffff0000, v155
	v_lshl_add_u64 v[190:191], s[10:11], 0, v[190:191]
	v_pk_mul_f32 v[154:155], v[142:143], v[154:155]
	v_pk_mul_f32 v[106:107], v[106:107], v[140:141]
	global_load_dwordx4 v[140:143], v[190:191], off
	v_lshlrev_b32_e32 v1, 16, v148
	v_pk_mul_f32 v[102:103], v[102:103], v[154:155]
	v_rcp_f32_e32 v154, v1
	v_and_b32_e32 v1, 0xffff0000, v148
	v_rcp_f32_e32 v155, v1
	v_lshlrev_b32_e32 v1, 16, v149
	v_rcp_f32_e32 v148, v1
	v_and_b32_e32 v1, 0xffff0000, v149
	v_pk_mul_f32 v[100:101], v[100:101], v[152:153]
	v_lshlrev_b32_e32 v152, 16, v132
	v_and_b32_e32 v153, 0xffff0000, v132
	v_rcp_f32_e32 v149, v1
	v_lshlrev_b32_e32 v1, 16, v150
	v_pk_mul_f32 v[152:153], v[154:155], v[152:153]
	v_rcp_f32_e32 v154, v1
	v_and_b32_e32 v1, 0xffff0000, v150
	v_rcp_f32_e32 v155, v1
	v_lshlrev_b32_e32 v132, 16, v133
	v_and_b32_e32 v133, 0xffff0000, v133
	v_pk_mul_f32 v[132:133], v[148:149], v[132:133]
	v_lshlrev_b32_e32 v148, 16, v134
	v_and_b32_e32 v149, 0xffff0000, v134
	v_lshlrev_b32_e32 v1, 16, v151
	v_pk_mul_f32 v[104:105], v[104:105], v[188:189]
	v_pk_mul_f32 v[154:155], v[154:155], v[148:149]
	v_rcp_f32_e32 v188, v1
	v_and_b32_e32 v1, 0xffff0000, v151
	global_load_dwordx4 v[148:151], v[192:193], off offset:256
	v_rcp_f32_e32 v189, v1
	v_lshlrev_b32_e32 v134, 16, v135
	v_and_b32_e32 v135, 0xffff0000, v135
	v_pk_mul_f32 v[98:99], v[98:99], v[132:133]
	v_pk_mul_f32 v[188:189], v[188:189], v[134:135]
	global_load_dwordx4 v[132:135], v[190:191], off offset:256
	s_waitcnt vmcnt(5)
	v_lshlrev_b32_e32 v1, 16, v144
	v_pk_mul_f32 v[96:97], v[96:97], v[152:153]
	v_rcp_f32_e32 v152, v1
	v_and_b32_e32 v1, 0xffff0000, v144
	v_rcp_f32_e32 v153, v1
	v_lshlrev_b32_e32 v1, 16, v145
	v_rcp_f32_e32 v144, v1
	v_and_b32_e32 v1, 0xffff0000, v145
	v_pk_mul_f32 v[92:93], v[92:93], v[154:155]
	s_waitcnt vmcnt(4)
	v_lshlrev_b32_e32 v154, 16, v136
	v_and_b32_e32 v155, 0xffff0000, v136
	v_rcp_f32_e32 v145, v1
	v_lshlrev_b32_e32 v1, 16, v146
	v_pk_mul_f32 v[94:95], v[94:95], v[188:189]
	v_pk_mul_f32 v[188:189], v[152:153], v[154:155]
	v_rcp_f32_e32 v152, v1
	v_and_b32_e32 v1, 0xffff0000, v146
	v_rcp_f32_e32 v153, v1
	v_lshlrev_b32_e32 v136, 16, v137
	v_and_b32_e32 v137, 0xffff0000, v137
	v_pk_mul_f32 v[136:137], v[144:145], v[136:137]
	v_lshlrev_b32_e32 v144, 16, v138
	v_and_b32_e32 v145, 0xffff0000, v138
	v_lshlrev_b32_e32 v1, 16, v147
	v_pk_mul_f32 v[190:191], v[152:153], v[144:145]
	v_rcp_f32_e32 v144, v1
	v_and_b32_e32 v1, 0xffff0000, v147
	v_lshl_add_u64 v[146:147], v[2:3], 0, s[6:7]
	v_lshl_add_u64 v[192:193], s[12:13], 0, v[146:147]
	v_rcp_f32_e32 v145, v1
	global_load_dwordx4 v[152:155], v[192:193], off
	v_lshlrev_b32_e32 v138, 16, v139
	v_and_b32_e32 v139, 0xffff0000, v139
	v_pk_mul_f32 v[138:139], v[144:145], v[138:139]
	v_pk_mul_f32 v[90:91], v[90:91], v[136:137]
	v_lshl_add_u64 v[136:137], s[10:11], 0, v[146:147]
	global_load_dwordx4 v[144:147], v[136:137], off
	s_waitcnt vmcnt(5)
	v_lshlrev_b32_e32 v1, 16, v184
	v_pk_mul_f32 v[86:87], v[86:87], v[138:139]
	v_rcp_f32_e32 v138, v1
	v_and_b32_e32 v1, 0xffff0000, v184
	v_rcp_f32_e32 v139, v1
	v_lshlrev_b32_e32 v1, 16, v185
	v_rcp_f32_e32 v184, v1
	v_and_b32_e32 v1, 0xffff0000, v185
	v_pk_mul_f32 v[88:89], v[88:89], v[188:189]
	s_waitcnt vmcnt(4)
	v_lshlrev_b32_e32 v188, 16, v140
	v_and_b32_e32 v189, 0xffff0000, v140
	v_rcp_f32_e32 v185, v1
	v_lshlrev_b32_e32 v1, 16, v186
	v_pk_mul_f32 v[138:139], v[138:139], v[188:189]
	v_rcp_f32_e32 v188, v1
	v_and_b32_e32 v1, 0xffff0000, v186
	v_rcp_f32_e32 v189, v1
	v_lshlrev_b32_e32 v140, 16, v141
	v_and_b32_e32 v141, 0xffff0000, v141
	v_pk_mul_f32 v[140:141], v[184:185], v[140:141]
	v_lshlrev_b32_e32 v184, 16, v142
	v_and_b32_e32 v185, 0xffff0000, v142
	v_lshlrev_b32_e32 v1, 16, v187
	v_pk_mul_f32 v[84:85], v[84:85], v[190:191]
	v_pk_mul_f32 v[188:189], v[188:189], v[184:185]
	v_rcp_f32_e32 v190, v1
	v_and_b32_e32 v1, 0xffff0000, v187
	global_load_dwordx4 v[184:187], v[192:193], off offset:256
	v_rcp_f32_e32 v191, v1
	v_lshlrev_b32_e32 v142, 16, v143
	v_and_b32_e32 v143, 0xffff0000, v143
	v_pk_mul_f32 v[82:83], v[82:83], v[140:141]
	v_pk_mul_f32 v[190:191], v[190:191], v[142:143]
	global_load_dwordx4 v[140:143], v[136:137], off offset:256
	v_pk_mul_f32 v[80:81], v[80:81], v[138:139]
	s_waitcnt vmcnt(5)
	v_lshlrev_b32_e32 v1, 16, v148
	v_rcp_f32_e32 v136, v1
	v_and_b32_e32 v1, 0xffff0000, v148
	v_rcp_f32_e32 v137, v1
	v_lshlrev_b32_e32 v1, 16, v149
	s_waitcnt vmcnt(4)
	v_lshlrev_b32_e32 v138, 16, v132
	v_and_b32_e32 v139, 0xffff0000, v132
	v_pk_mul_f32 v[136:137], v[136:137], v[138:139]
	v_rcp_f32_e32 v138, v1
	v_and_b32_e32 v1, 0xffff0000, v149
	v_rcp_f32_e32 v139, v1
	v_lshlrev_b32_e32 v1, 16, v150
	v_rcp_f32_e32 v148, v1
	v_and_b32_e32 v1, 0xffff0000, v150
	v_rcp_f32_e32 v149, v1
	v_lshlrev_b32_e32 v132, 16, v133
	v_and_b32_e32 v133, 0xffff0000, v133
	v_pk_mul_f32 v[132:133], v[138:139], v[132:133]
	v_lshlrev_b32_e32 v138, 16, v134
	v_and_b32_e32 v139, 0xffff0000, v134
	v_lshlrev_b32_e32 v1, 16, v151
	v_pk_mul_f32 v[138:139], v[148:149], v[138:139]
	v_rcp_f32_e32 v148, v1
	v_and_b32_e32 v1, 0xffff0000, v151
	v_rcp_f32_e32 v149, v1
	v_lshlrev_b32_e32 v134, 16, v135
	v_and_b32_e32 v135, 0xffff0000, v135
	v_lshl_add_u64 v[150:151], v[2:3], 0, s[24:25]
	v_pk_mul_f32 v[134:135], v[148:149], v[134:135]
	v_lshl_add_u64 v[192:193], s[12:13], 0, v[150:151]
	v_pk_mul_f32 v[70:71], v[70:71], v[134:135]
	v_pk_mul_f32 v[78:79], v[78:79], v[190:191]
	v_pk_mul_f32 v[76:77], v[76:77], v[188:189]
	global_load_dwordx4 v[188:191], v[192:193], off
	v_pk_mul_f32 v[72:73], v[72:73], v[136:137]
	v_pk_mul_f32 v[74:75], v[74:75], v[132:133]
	v_lshl_add_u64 v[132:133], s[10:11], 0, v[150:151]
	s_waitcnt vmcnt(4)
	v_lshlrev_b32_e32 v1, 16, v152
	v_rcp_f32_e32 v134, v1
	v_and_b32_e32 v1, 0xffff0000, v152
	v_rcp_f32_e32 v135, v1
	v_lshlrev_b32_e32 v1, 16, v153
	global_load_dwordx4 v[148:151], v[132:133], off
	s_waitcnt vmcnt(4)
	v_lshlrev_b32_e32 v136, 16, v144
	v_and_b32_e32 v137, 0xffff0000, v144
	v_pk_mul_f32 v[194:195], v[134:135], v[136:137]
	v_rcp_f32_e32 v134, v1
	v_and_b32_e32 v1, 0xffff0000, v153
	v_rcp_f32_e32 v135, v1
	v_lshlrev_b32_e32 v1, 16, v154
	v_pk_mul_f32 v[68:69], v[68:69], v[138:139]
	v_rcp_f32_e32 v138, v1
	v_and_b32_e32 v1, 0xffff0000, v154
	v_rcp_f32_e32 v139, v1
	v_lshlrev_b32_e32 v1, 16, v155
	v_rcp_f32_e32 v152, v1
	v_and_b32_e32 v1, 0xffff0000, v155
	v_rcp_f32_e32 v153, v1
	v_lshlrev_b32_e32 v136, 16, v145
	v_and_b32_e32 v137, 0xffff0000, v145
	v_pk_mul_f32 v[134:135], v[134:135], v[136:137]
	v_lshlrev_b32_e32 v136, 16, v146
	v_and_b32_e32 v137, 0xffff0000, v146
	v_lshlrev_b32_e32 v146, 16, v147
	v_and_b32_e32 v147, 0xffff0000, v147
	v_pk_mul_f32 v[146:147], v[152:153], v[146:147]
	v_pk_mul_f32 v[144:145], v[138:139], v[136:137]
	v_pk_mul_f32 v[62:63], v[62:63], v[146:147]
	global_load_dwordx4 v[136:139], v[192:193], off offset:256
	v_pk_mul_f32 v[60:61], v[60:61], v[144:145]
	v_pk_mul_f32 v[66:67], v[66:67], v[134:135]
	s_waitcnt vmcnt(4)
	v_lshlrev_b32_e32 v1, 16, v184
	v_rcp_f32_e32 v146, v1
	v_and_b32_e32 v1, 0xffff0000, v184
	v_rcp_f32_e32 v147, v1
	v_lshlrev_b32_e32 v1, 16, v185
	global_load_dwordx4 v[132:135], v[132:133], off offset:256
	s_waitcnt vmcnt(4)
	v_lshlrev_b32_e32 v144, 16, v140
	v_and_b32_e32 v145, 0xffff0000, v140
	v_pk_mul_f32 v[152:153], v[146:147], v[144:145]
	v_rcp_f32_e32 v144, v1
	v_and_b32_e32 v1, 0xffff0000, v185
	v_rcp_f32_e32 v145, v1
	v_lshlrev_b32_e32 v1, 16, v186
	v_rcp_f32_e32 v146, v1
	v_and_b32_e32 v1, 0xffff0000, v186
	v_rcp_f32_e32 v147, v1
	v_lshlrev_b32_e32 v1, 16, v187
	v_lshlrev_b32_e32 v140, 16, v141
	v_and_b32_e32 v141, 0xffff0000, v141
	v_rcp_f32_e32 v184, v1
	v_and_b32_e32 v1, 0xffff0000, v187
	v_lshl_add_u64 v[186:187], v[2:3], 0, s[26:27]
	v_pk_mul_f32 v[140:141], v[144:145], v[140:141]
	v_lshlrev_b32_e32 v144, 16, v142
	v_and_b32_e32 v145, 0xffff0000, v142
	v_lshl_add_u64 v[192:193], s[12:13], 0, v[186:187]
	v_pk_mul_f32 v[154:155], v[146:147], v[144:145]
	global_load_dwordx4 v[144:147], v[192:193], off
	v_rcp_f32_e32 v185, v1
	v_lshlrev_b32_e32 v142, 16, v143
	v_and_b32_e32 v143, 0xffff0000, v143
	v_lshl_add_u64 v[186:187], s[10:11], 0, v[186:187]
	v_pk_mul_f32 v[184:185], v[184:185], v[142:143]
	v_pk_mul_f32 v[58:59], v[58:59], v[140:141]
	global_load_dwordx4 v[140:143], v[186:187], off
	v_pk_mul_f32 v[56:57], v[56:57], v[152:153]
	v_pk_mul_f32 v[52:53], v[52:53], v[154:155]
	v_pk_mul_f32 v[54:55], v[54:55], v[184:185]
	v_lshl_add_u64 v[2:3], v[2:3], 0, s[28:29]
	v_pk_mul_f32 v[64:65], v[64:65], v[194:195]
	v_lshl_add_u64 v[194:195], s[12:13], 0, v[2:3]
	s_waitcnt vmcnt(5)
	v_lshlrev_b32_e32 v1, 16, v188
	v_rcp_f32_e32 v152, v1
	v_and_b32_e32 v1, 0xffff0000, v188
	v_rcp_f32_e32 v153, v1
	v_lshlrev_b32_e32 v1, 16, v189
	v_lshl_add_u64 v[2:3], s[10:11], 0, v[2:3]
	s_waitcnt vmcnt(4)
	v_lshlrev_b32_e32 v154, 16, v148
	v_and_b32_e32 v155, 0xffff0000, v148
	v_pk_mul_f32 v[184:185], v[152:153], v[154:155]
	v_rcp_f32_e32 v152, v1
	v_and_b32_e32 v1, 0xffff0000, v189
	v_rcp_f32_e32 v153, v1
	v_lshlrev_b32_e32 v1, 16, v190
	v_rcp_f32_e32 v154, v1
	v_and_b32_e32 v1, 0xffff0000, v190
	v_rcp_f32_e32 v155, v1
	v_lshlrev_b32_e32 v148, 16, v149
	v_and_b32_e32 v149, 0xffff0000, v149
	v_pk_mul_f32 v[148:149], v[152:153], v[148:149]
	v_lshlrev_b32_e32 v152, 16, v150
	v_and_b32_e32 v153, 0xffff0000, v150
	v_pk_mul_f32 v[188:189], v[154:155], v[152:153]
	v_lshlrev_b32_e32 v1, 16, v191
	global_load_dwordx4 v[152:155], v[192:193], off offset:256
	v_rcp_f32_e32 v190, v1
	v_and_b32_e32 v1, 0xffff0000, v191
	v_rcp_f32_e32 v191, v1
	v_lshlrev_b32_e32 v150, 16, v151
	v_and_b32_e32 v151, 0xffff0000, v151
	v_pk_mul_f32 v[48:49], v[48:49], v[184:185]
	v_pk_mul_f32 v[190:191], v[190:191], v[150:151]
	v_pk_mul_f32 v[50:51], v[50:51], v[148:149]
	s_waitcnt vmcnt(4)
	v_lshlrev_b32_e32 v1, 16, v136
	v_rcp_f32_e32 v184, v1
	v_and_b32_e32 v1, 0xffff0000, v136
	global_load_dwordx4 v[148:151], v[186:187], off offset:256
	v_rcp_f32_e32 v185, v1
	v_lshlrev_b32_e32 v1, 16, v137
	v_rcp_f32_e32 v136, v1
	v_and_b32_e32 v1, 0xffff0000, v137
	v_rcp_f32_e32 v137, v1
	v_lshlrev_b32_e32 v1, 16, v138
	v_pk_mul_f32 v[46:47], v[46:47], v[190:191]
	v_rcp_f32_e32 v190, v1
	v_and_b32_e32 v1, 0xffff0000, v138
	s_waitcnt vmcnt(4)
	v_lshlrev_b32_e32 v186, 16, v132
	v_and_b32_e32 v187, 0xffff0000, v132
	v_rcp_f32_e32 v191, v1
	v_lshlrev_b32_e32 v1, 16, v139
	v_pk_mul_f32 v[44:45], v[44:45], v[188:189]
	v_pk_mul_f32 v[188:189], v[184:185], v[186:187]
	v_lshlrev_b32_e32 v132, 16, v133
	v_and_b32_e32 v133, 0xffff0000, v133
	global_load_dwordx4 v[184:187], v[194:195], off
	v_rcp_f32_e32 v196, v1
	v_and_b32_e32 v1, 0xffff0000, v139
	v_pk_mul_f32 v[132:133], v[136:137], v[132:133]
	v_rcp_f32_e32 v197, v1
	v_pk_mul_f32 v[42:43], v[42:43], v[132:133]
	v_lshlrev_b32_e32 v192, 16, v134
	v_and_b32_e32 v193, 0xffff0000, v134
	global_load_dwordx4 v[136:139], v[2:3], off
	s_waitcnt vmcnt(5)
	v_lshlrev_b32_e32 v1, 16, v144
	v_rcp_f32_e32 v132, v1
	v_and_b32_e32 v1, 0xffff0000, v144
	v_rcp_f32_e32 v133, v1
	v_lshlrev_b32_e32 v1, 16, v145
	v_rcp_f32_e32 v144, v1
	v_and_b32_e32 v1, 0xffff0000, v145
	v_lshlrev_b32_e32 v134, 16, v135
	v_and_b32_e32 v135, 0xffff0000, v135
	v_rcp_f32_e32 v145, v1
	v_pk_mul_f32 v[134:135], v[196:197], v[134:135]
	v_pk_mul_f32 v[190:191], v[190:191], v[192:193]
	v_pk_mul_f32 v[38:39], v[38:39], v[134:135]
	s_waitcnt vmcnt(4)
	v_lshlrev_b32_e32 v134, 16, v140
	v_and_b32_e32 v135, 0xffff0000, v140
	v_pk_mul_f32 v[192:193], v[132:133], v[134:135]
	v_lshlrev_b32_e32 v132, 16, v141
	v_and_b32_e32 v133, 0xffff0000, v141
	v_pk_mul_f32 v[140:141], v[144:145], v[132:133]
	global_load_dwordx4 v[132:135], v[194:195], off offset:256
	v_pk_mul_f32 v[40:41], v[40:41], v[188:189]
	v_pk_mul_f32 v[36:37], v[36:37], v[190:191]
	global_load_dwordx4 v[188:191], v[2:3], off offset:256
	v_lshlrev_b32_e32 v1, 16, v146
	v_rcp_f32_e32 v144, v1
	v_and_b32_e32 v1, 0xffff0000, v146
	v_rcp_f32_e32 v145, v1
	v_lshlrev_b32_e32 v1, 16, v147
	v_rcp_f32_e32 v2, v1
	v_and_b32_e32 v1, 0xffff0000, v147
	v_rcp_f32_e32 v3, v1
	v_lshlrev_b32_e32 v194, 16, v142
	v_and_b32_e32 v195, 0xffff0000, v142
	v_lshlrev_b32_e32 v142, 16, v143
	v_and_b32_e32 v143, 0xffff0000, v143
	v_pk_mul_f32 v[2:3], v[2:3], v[142:143]
	v_pk_mul_f32 v[34:35], v[34:35], v[140:141]
	v_pk_mul_f32 v[30:31], v[30:31], v[2:3]
	v_pk_mul_f32 v[144:145], v[144:145], v[194:195]
	s_waitcnt vmcnt(5)
	v_lshlrev_b32_e32 v1, 16, v152
	v_rcp_f32_e32 v2, v1
	v_and_b32_e32 v1, 0xffff0000, v152
	v_rcp_f32_e32 v3, v1
	v_lshlrev_b32_e32 v1, 16, v153
	v_rcp_f32_e32 v142, v1
	v_and_b32_e32 v1, 0xffff0000, v153
	v_rcp_f32_e32 v143, v1
	v_lshlrev_b32_e32 v1, 16, v154
	v_pk_mul_f32 v[28:29], v[28:29], v[144:145]
	v_pk_mul_f32 v[32:33], v[32:33], v[192:193]
	s_waitcnt vmcnt(4)
	v_lshlrev_b32_e32 v140, 16, v148
	v_and_b32_e32 v141, 0xffff0000, v148
	v_pk_mul_f32 v[2:3], v[2:3], v[140:141]
	v_lshlrev_b32_e32 v140, 16, v149
	v_and_b32_e32 v141, 0xffff0000, v149
	v_pk_mul_f32 v[140:141], v[142:143], v[140:141]
	v_rcp_f32_e32 v142, v1
	v_and_b32_e32 v1, 0xffff0000, v154
	v_rcp_f32_e32 v143, v1
	v_lshlrev_b32_e32 v1, 16, v155
	v_rcp_f32_e32 v146, v1
	v_and_b32_e32 v1, 0xffff0000, v155
	v_rcp_f32_e32 v147, v1
	v_pk_mul_f32 v[24:25], v[24:25], v[2:3]
	v_lshlrev_b32_e32 v144, 16, v150
	v_and_b32_e32 v145, 0xffff0000, v150
	v_pk_mul_f32 v[142:143], v[142:143], v[144:145]
	v_pk_mul_f32 v[26:27], v[26:27], v[140:141]
	v_pk_mul_f32 v[20:21], v[20:21], v[142:143]
	s_waitcnt vmcnt(3)
	v_lshlrev_b32_e32 v1, 16, v184
	v_rcp_f32_e32 v2, v1
	v_and_b32_e32 v1, 0xffff0000, v184
	v_rcp_f32_e32 v3, v1
	v_lshlrev_b32_e32 v1, 16, v185
	v_rcp_f32_e32 v142, v1
	v_and_b32_e32 v1, 0xffff0000, v185
	v_rcp_f32_e32 v143, v1
	s_waitcnt vmcnt(2)
	v_lshlrev_b32_e32 v140, 16, v136
	v_and_b32_e32 v141, 0xffff0000, v136
	v_lshlrev_b32_e32 v1, 16, v186
	v_lshlrev_b32_e32 v144, 16, v151
	v_and_b32_e32 v145, 0xffff0000, v151
	v_pk_mul_f32 v[2:3], v[2:3], v[140:141]
	v_rcp_f32_e32 v140, v1
	v_and_b32_e32 v1, 0xffff0000, v186
	v_pk_mul_f32 v[144:145], v[146:147], v[144:145]
	v_rcp_f32_e32 v141, v1
	v_lshlrev_b32_e32 v1, 16, v187
	v_pk_mul_f32 v[22:23], v[22:23], v[144:145]
	v_rcp_f32_e32 v144, v1
	v_and_b32_e32 v1, 0xffff0000, v187
	v_rcp_f32_e32 v145, v1
	v_pk_mul_f32 v[16:17], v[16:17], v[2:3]
	v_lshlrev_b32_e32 v136, 16, v137
	v_and_b32_e32 v137, 0xffff0000, v137
	v_pk_mul_f32 v[136:137], v[142:143], v[136:137]
	v_lshlrev_b32_e32 v142, 16, v138
	s_waitcnt vmcnt(1)
	v_lshlrev_b32_e32 v1, 16, v132
	v_rcp_f32_e32 v2, v1
	v_and_b32_e32 v1, 0xffff0000, v132
	v_rcp_f32_e32 v3, v1
	v_lshlrev_b32_e32 v1, 16, v133
	v_rcp_f32_e32 v132, v1
	v_and_b32_e32 v1, 0xffff0000, v133
	v_rcp_f32_e32 v133, v1
	v_pk_mul_f32 v[18:19], v[18:19], v[136:137]
	s_waitcnt vmcnt(0)
	v_lshlrev_b32_e32 v136, 16, v188
	v_and_b32_e32 v137, 0xffff0000, v188
	v_pk_mul_f32 v[2:3], v[2:3], v[136:137]
	v_lshlrev_b32_e32 v136, 16, v189
	v_and_b32_e32 v137, 0xffff0000, v189
	v_lshlrev_b32_e32 v1, 16, v134
	v_pk_mul_f32 v[132:133], v[132:133], v[136:137]
	v_rcp_f32_e32 v136, v1
	v_and_b32_e32 v1, 0xffff0000, v134
	v_rcp_f32_e32 v137, v1
	v_lshlrev_b32_e32 v1, 16, v135
	v_rcp_f32_e32 v134, v1
	v_and_b32_e32 v1, 0xffff0000, v135
	v_and_b32_e32 v143, 0xffff0000, v138
	v_lshlrev_b32_e32 v138, 16, v139
	v_and_b32_e32 v139, 0xffff0000, v139
	v_rcp_f32_e32 v135, v1
	v_pk_mul_f32 v[138:139], v[144:145], v[138:139]
	v_pk_mul_f32 v[140:141], v[140:141], v[142:143]
	v_pk_mul_f32 v[14:15], v[14:15], v[138:139]
	v_lshlrev_b32_e32 v138, 16, v190
	v_and_b32_e32 v139, 0xffff0000, v190
	v_pk_mul_f32 v[136:137], v[136:137], v[138:139]
	v_lshlrev_b32_e32 v138, 16, v191
	v_and_b32_e32 v139, 0xffff0000, v191
	v_pk_mul_f32 v[134:135], v[134:135], v[138:139]
	v_pk_mul_f32 v[12:13], v[12:13], v[140:141]
	v_pk_mul_f32 v[10:11], v[10:11], v[132:133]
	v_pk_mul_f32 v[8:9], v[8:9], v[2:3]
	v_pk_mul_f32 v[6:7], v[6:7], v[134:135]
	v_pk_mul_f32 v[4:5], v[4:5], v[136:137]
	s_andn2_b64 vcc, exec, s[8:9]
	s_cbranch_vccnz .Lmid_align_b
	s_barrier
.Lmid_align_b:
	s_branch .LBB0_502
